# gate GEMM epilogue hand-rewritten with 4 row groups of loads in flight (counted vmcnt), on top of v4
# speedup vs baseline: 1.0351x; 1.0066x over previous
;     __device__ __forceinline__ void operator()(const f32x4 (&acc)[2][2][4][2], const Unit& u, int wr, int wc, int fr, int fq) const {
;     ...
;             for (int m = 0; m < 4; ++m) { const int row = row0 + ai * HALF + m * 16; const size_t off = (size_t)row * ldc + col0;
;                 const float nrl = -1.4426950408889634f * __builtin_amdgcn_rsqf(__hip_atomic_load(rowsq + row, __ATOMIC_RELAXED, __HIP_MEMORY_SCOPE_AGENT) * (1.f / (float)ldc) + eps);
; #pragma unroll
;                 for (int bj = 0; bj < 2; ++bj) { const size_t o2 = off + bj * HALF; const u32x4 xw = *(const u32x4*)(xb + o2), g = *(const u32x4*)(pl + o2);
;                     f32x4 b0, b1, p0, p1;
;                     b0[0] = __uint_as_float(xw.x << 16); b0[1] = __uint_as_float(xw.x & 0xffff0000u); b0[2] = __uint_as_float(xw.y << 16); b0[3] = __uint_as_float(xw.y & 0xffff0000u);
;                     b1[0] = __uint_as_float(xw.z << 16); b1[1] = __uint_as_float(xw.z & 0xffff0000u); b1[2] = __uint_as_float(xw.w << 16); b1[3] = __uint_as_float(xw.w & 0xffff0000u);
;                     p0[0] = __uint_as_float(g.x << 16); p0[1] = __uint_as_float(g.x & 0xffff0000u); p0[2] = __uint_as_float(g.y << 16); p0[3] = __uint_as_float(g.y & 0xffff0000u);
;                     p1[0] = __uint_as_float(g.z << 16); p1[1] = __uint_as_float(g.z & 0xffff0000u); p1[2] = __uint_as_float(g.w << 16); p1[3] = __uint_as_float(g.w & 0xffff0000u);
;                     f32x4 s0, s1;
; #pragma unroll
;                     for (int e = 0; e < 4; ++e) { s0[e] = __builtin_amdgcn_rcpf(1.f + __builtin_amdgcn_exp2f(nrl * acc[ai][bj][m][0][e])); s1[e] = __builtin_amdgcn_rcpf(1.f + __builtin_amdgcn_exp2f(nrl * acc[ai][bj][m][1][e])); }
;                     *(f32x4*)(out + o2) = b0 + s0 * p0; *(f32x4*)(out + o2 + 4) = b1 + s1 * p1; }
.LBB0_727:
	s_lshl_b32 s8, s38, 8
	s_add_i32 s8, s8, s55
	s_lshl_b32 s2, s2, 8
	s_or_b32 s2, s2, s56
	v_add_u32_e32 v144, s8, v148
	v_lshl_add_u32 v145, v149, 3, s2
	v_lshl_add_u32 v146, v144, 10, v145
	v_lshlrev_b32_e32 v156, 2, v144
	v_lshlrev_b32_e32 v147, 1, v146
	v_lshlrev_b32_e32 v155, 2, v146
	s_andn2_b64 vcc, exec, s[0:1]
	s_mov_b64 s[0:1], -1
	s_mov_b64 s[72:73], s[46:47]
	s_mov_b64 s[74:75], s[6:7]
	global_load_dword v198, v156, s[70:71] sc1
	global_load_dwordx4 v[182:185], v147, s[72:73]
	global_load_dwordx4 v[190:193], v147, s[74:75]
	global_load_dwordx4 v[186:189], v147, s[72:73] offset:256
	global_load_dwordx4 v[194:197], v147, s[74:75] offset:256
	s_add_u32 s72, s46, 0x8000
	s_addc_u32 s73, s47, 0
	s_add_u32 s74, s6, 0x8000
	s_addc_u32 s75, s7, 0
	global_load_dword v216, v156, s[70:71] offset:64 sc1
	global_load_dwordx4 v[200:203], v147, s[72:73]
	global_load_dwordx4 v[208:211], v147, s[74:75]
	global_load_dwordx4 v[204:207], v147, s[72:73] offset:256
	global_load_dwordx4 v[212:215], v147, s[74:75] offset:256
	s_add_u32 s72, s46, 0x10000
	s_addc_u32 s73, s47, 0
	s_add_u32 s74, s6, 0x10000
	s_addc_u32 s75, s7, 0
	global_load_dword v234, v156, s[70:71] offset:128 sc1
	global_load_dwordx4 v[218:221], v147, s[72:73]
	global_load_dwordx4 v[226:229], v147, s[74:75]
	global_load_dwordx4 v[222:225], v147, s[72:73] offset:256
	global_load_dwordx4 v[230:233], v147, s[74:75] offset:256
	s_add_u32 s72, s46, 0x18000
	s_addc_u32 s73, s47, 0
	s_add_u32 s74, s6, 0x18000
	s_addc_u32 s75, s7, 0
	global_load_dword v252, v156, s[70:71] offset:192 sc1
	global_load_dwordx4 v[236:239], v147, s[72:73]
	global_load_dwordx4 v[244:247], v147, s[74:75]
	global_load_dwordx4 v[240:243], v147, s[72:73] offset:256
	global_load_dwordx4 v[248:251], v147, s[74:75] offset:256
	s_waitcnt vmcnt(15)
	v_fmamk_f32 v157, v198, 0x3a800000, v154
	v_rsq_f32_e32 v157, v157
	s_mov_b64 s[76:77], s[80:81]
	s_nop 0
	v_mul_f32_e32 v157, 0xbfb8aa3b, v157
	v_mul_f32_e32 v120, v120, v157
	v_mul_f32_e32 v121, v121, v157
	v_mul_f32_e32 v122, v122, v157
	v_mul_f32_e32 v123, v123, v157
	v_mul_f32_e32 v124, v124, v157
	v_mul_f32_e32 v125, v125, v157
	v_mul_f32_e32 v126, v126, v157
	v_mul_f32_e32 v127, v127, v157
	v_exp_f32_e32 v120, v120
	v_exp_f32_e32 v121, v121
	v_exp_f32_e32 v122, v122
	v_exp_f32_e32 v123, v123
	v_exp_f32_e32 v124, v124
	v_exp_f32_e32 v125, v125
	v_exp_f32_e32 v126, v126
	v_exp_f32_e32 v127, v127
	v_add_f32_e32 v120, 1.0, v120
	v_add_f32_e32 v121, 1.0, v121
	v_add_f32_e32 v122, 1.0, v122
	v_add_f32_e32 v123, 1.0, v123
	v_add_f32_e32 v124, 1.0, v124
	v_add_f32_e32 v125, 1.0, v125
	v_add_f32_e32 v126, 1.0, v126
	v_add_f32_e32 v127, 1.0, v127
	v_rcp_f32_e32 v120, v120
	v_rcp_f32_e32 v121, v121
	v_rcp_f32_e32 v122, v122
	v_rcp_f32_e32 v123, v123
	v_rcp_f32_e32 v124, v124
	v_rcp_f32_e32 v125, v125
	v_rcp_f32_e32 v126, v126
	v_rcp_f32_e32 v127, v127
	v_lshlrev_b32_e32 v158, 16, v182
	v_and_b32_e32 v159, 0xffff0000, v182
	v_lshlrev_b32_e32 v166, 16, v190
	v_and_b32_e32 v167, 0xffff0000, v190
	v_lshlrev_b32_e32 v160, 16, v183
	v_and_b32_e32 v161, 0xffff0000, v183
	v_lshlrev_b32_e32 v168, 16, v191
	v_and_b32_e32 v169, 0xffff0000, v191
	v_lshlrev_b32_e32 v162, 16, v184
	v_and_b32_e32 v163, 0xffff0000, v184
	v_lshlrev_b32_e32 v170, 16, v192
	v_and_b32_e32 v171, 0xffff0000, v192
	v_lshlrev_b32_e32 v164, 16, v185
	v_and_b32_e32 v165, 0xffff0000, v185
	v_lshlrev_b32_e32 v172, 16, v193
	v_and_b32_e32 v173, 0xffff0000, v193
	v_pk_fma_f32 v[124:125], v[124:125], v[166:167], v[158:159]
	v_pk_fma_f32 v[126:127], v[126:127], v[168:169], v[160:161]
	v_pk_fma_f32 v[120:121], v[120:121], v[170:171], v[162:163]
	v_pk_fma_f32 v[122:123], v[122:123], v[172:173], v[164:165]
	global_store_dwordx4 v155, v[124:127], s[76:77]
	global_store_dwordx4 v155, v[120:123], s[76:77] offset:16
	v_mul_f32_e32 v112, v112, v157
	v_mul_f32_e32 v113, v113, v157
	v_mul_f32_e32 v114, v114, v157
	v_mul_f32_e32 v115, v115, v157
	v_mul_f32_e32 v116, v116, v157
	v_mul_f32_e32 v117, v117, v157
	v_mul_f32_e32 v118, v118, v157
	v_mul_f32_e32 v119, v119, v157
	v_exp_f32_e32 v112, v112
	v_exp_f32_e32 v113, v113
	v_exp_f32_e32 v114, v114
	v_exp_f32_e32 v115, v115
	v_exp_f32_e32 v116, v116
	v_exp_f32_e32 v117, v117
	v_exp_f32_e32 v118, v118
	v_exp_f32_e32 v119, v119
	v_add_f32_e32 v112, 1.0, v112
	v_add_f32_e32 v113, 1.0, v113
	v_add_f32_e32 v114, 1.0, v114
	v_add_f32_e32 v115, 1.0, v115
	v_add_f32_e32 v116, 1.0, v116
	v_add_f32_e32 v117, 1.0, v117
	v_add_f32_e32 v118, 1.0, v118
	v_add_f32_e32 v119, 1.0, v119
	v_rcp_f32_e32 v112, v112
	v_rcp_f32_e32 v113, v113
	v_rcp_f32_e32 v114, v114
	v_rcp_f32_e32 v115, v115
	v_rcp_f32_e32 v116, v116
	v_rcp_f32_e32 v117, v117
	v_rcp_f32_e32 v118, v118
	v_rcp_f32_e32 v119, v119
	v_lshlrev_b32_e32 v158, 16, v186
	v_and_b32_e32 v159, 0xffff0000, v186
	v_lshlrev_b32_e32 v166, 16, v194
	v_and_b32_e32 v167, 0xffff0000, v194
	v_lshlrev_b32_e32 v160, 16, v187
	v_and_b32_e32 v161, 0xffff0000, v187
	v_lshlrev_b32_e32 v168, 16, v195
	v_and_b32_e32 v169, 0xffff0000, v195
	v_lshlrev_b32_e32 v162, 16, v188
	v_and_b32_e32 v163, 0xffff0000, v188
	v_lshlrev_b32_e32 v170, 16, v196
	v_and_b32_e32 v171, 0xffff0000, v196
	v_lshlrev_b32_e32 v164, 16, v189
	v_and_b32_e32 v165, 0xffff0000, v189
	v_lshlrev_b32_e32 v172, 16, v197
	v_and_b32_e32 v173, 0xffff0000, v197
	v_pk_fma_f32 v[116:117], v[116:117], v[166:167], v[158:159]
	v_pk_fma_f32 v[118:119], v[118:119], v[168:169], v[160:161]
	v_pk_fma_f32 v[112:113], v[112:113], v[170:171], v[162:163]
	v_pk_fma_f32 v[114:115], v[114:115], v[172:173], v[164:165]
	global_store_dwordx4 v155, v[116:119], s[76:77] offset:512
	global_store_dwordx4 v155, v[112:115], s[76:77] offset:528
	s_add_u32 s72, s46, 0x40000
	s_addc_u32 s73, s47, 0
	s_add_u32 s74, s6, 0x40000
	s_addc_u32 s75, s7, 0
	global_load_dword v198, v156, s[70:71] offset:512 sc1
	global_load_dwordx4 v[182:185], v147, s[72:73]
	global_load_dwordx4 v[190:193], v147, s[74:75]
	global_load_dwordx4 v[186:189], v147, s[72:73] offset:256
	global_load_dwordx4 v[194:197], v147, s[74:75] offset:256
	s_waitcnt vmcnt(19)
;     __device__ __forceinline__ void operator()(const f32x4 (&acc)[2][2][4][2], const Unit& u, int wr, int wc, int fr, int fq) const {
;     ...
;             for (int m = 0; m < 4; ++m) { const int row = row0 + ai * HALF + m * 16; const size_t off = (size_t)row * ldc + col0;
;                 const float nrl = -1.4426950408889634f * __builtin_amdgcn_rsqf(__hip_atomic_load(rowsq + row, __ATOMIC_RELAXED, __HIP_MEMORY_SCOPE_AGENT) * (1.f / (float)ldc) + eps);
; #pragma unroll
;                 for (int bj = 0; bj < 2; ++bj) { const size_t o2 = off + bj * HALF; const u32x4 xw = *(const u32x4*)(xb + o2), g = *(const u32x4*)(pl + o2);
;                     f32x4 b0, b1, p0, p1;
;                     b0[0] = __uint_as_float(xw.x << 16); b0[1] = __uint_as_float(xw.x & 0xffff0000u); b0[2] = __uint_as_float(xw.y << 16); b0[3] = __uint_as_float(xw.y & 0xffff0000u);
;                     b1[0] = __uint_as_float(xw.z << 16); b1[1] = __uint_as_float(xw.z & 0xffff0000u); b1[2] = __uint_as_float(xw.w << 16); b1[3] = __uint_as_float(xw.w & 0xffff0000u);
;                     p0[0] = __uint_as_float(g.x << 16); p0[1] = __uint_as_float(g.x & 0xffff0000u); p0[2] = __uint_as_float(g.y << 16); p0[3] = __uint_as_float(g.y & 0xffff0000u);
;                     p1[0] = __uint_as_float(g.z << 16); p1[1] = __uint_as_float(g.z & 0xffff0000u); p1[2] = __uint_as_float(g.w << 16); p1[3] = __uint_as_float(g.w & 0xffff0000u);
;                     f32x4 s0, s1;
; #pragma unroll
;                     for (int e = 0; e < 4; ++e) { s0[e] = __builtin_amdgcn_rcpf(1.f + __builtin_amdgcn_exp2f(nrl * acc[ai][bj][m][0][e])); s1[e] = __builtin_amdgcn_rcpf(1.f + __builtin_amdgcn_exp2f(nrl * acc[ai][bj][m][1][e])); }
;                     *(f32x4*)(out + o2) = b0 + s0 * p0; *(f32x4*)(out + o2 + 4) = b1 + s1 * p1; }
	v_fmamk_f32 v157, v216, 0x3a800000, v154
	v_rsq_f32_e32 v157, v157
	s_add_u32 s76, s80, 0x10000
	s_addc_u32 s77, s81, 0
	v_mul_f32_e32 v157, 0xbfb8aa3b, v157
	v_mul_f32_e32 v104, v104, v157
	v_mul_f32_e32 v105, v105, v157
	v_mul_f32_e32 v106, v106, v157
	v_mul_f32_e32 v107, v107, v157
	v_mul_f32_e32 v108, v108, v157
	v_mul_f32_e32 v109, v109, v157
	v_mul_f32_e32 v110, v110, v157
	v_mul_f32_e32 v111, v111, v157
	v_exp_f32_e32 v104, v104
	v_exp_f32_e32 v105, v105
	v_exp_f32_e32 v106, v106
	v_exp_f32_e32 v107, v107
	v_exp_f32_e32 v108, v108
	v_exp_f32_e32 v109, v109
	v_exp_f32_e32 v110, v110
	v_exp_f32_e32 v111, v111
	v_add_f32_e32 v104, 1.0, v104
	v_add_f32_e32 v105, 1.0, v105
	v_add_f32_e32 v106, 1.0, v106
	v_add_f32_e32 v107, 1.0, v107
	v_add_f32_e32 v108, 1.0, v108
	v_add_f32_e32 v109, 1.0, v109
	v_add_f32_e32 v110, 1.0, v110
	v_add_f32_e32 v111, 1.0, v111
	v_rcp_f32_e32 v104, v104
	v_rcp_f32_e32 v105, v105
	v_rcp_f32_e32 v106, v106
	v_rcp_f32_e32 v107, v107
	v_rcp_f32_e32 v108, v108
	v_rcp_f32_e32 v109, v109
	v_rcp_f32_e32 v110, v110
	v_rcp_f32_e32 v111, v111
	v_lshlrev_b32_e32 v158, 16, v200
	v_and_b32_e32 v159, 0xffff0000, v200
	v_lshlrev_b32_e32 v166, 16, v208
	v_and_b32_e32 v167, 0xffff0000, v208
	v_lshlrev_b32_e32 v160, 16, v201
	v_and_b32_e32 v161, 0xffff0000, v201
	v_lshlrev_b32_e32 v168, 16, v209
	v_and_b32_e32 v169, 0xffff0000, v209
	v_lshlrev_b32_e32 v162, 16, v202
	v_and_b32_e32 v163, 0xffff0000, v202
	v_lshlrev_b32_e32 v170, 16, v210
	v_and_b32_e32 v171, 0xffff0000, v210
	v_lshlrev_b32_e32 v164, 16, v203
	v_and_b32_e32 v165, 0xffff0000, v203
	v_lshlrev_b32_e32 v172, 16, v211
	v_and_b32_e32 v173, 0xffff0000, v211
	v_pk_fma_f32 v[108:109], v[108:109], v[166:167], v[158:159]
	v_pk_fma_f32 v[110:111], v[110:111], v[168:169], v[160:161]
	v_pk_fma_f32 v[104:105], v[104:105], v[170:171], v[162:163]
	v_pk_fma_f32 v[106:107], v[106:107], v[172:173], v[164:165]
	global_store_dwordx4 v155, v[108:111], s[76:77]
	global_store_dwordx4 v155, v[104:107], s[76:77] offset:16
	v_mul_f32_e32 v96, v96, v157
	v_mul_f32_e32 v97, v97, v157
	v_mul_f32_e32 v98, v98, v157
	v_mul_f32_e32 v99, v99, v157
	v_mul_f32_e32 v100, v100, v157
	v_mul_f32_e32 v101, v101, v157
	v_mul_f32_e32 v102, v102, v157
	v_mul_f32_e32 v103, v103, v157
	v_exp_f32_e32 v96, v96
	v_exp_f32_e32 v97, v97
	v_exp_f32_e32 v98, v98
	v_exp_f32_e32 v99, v99
	v_exp_f32_e32 v100, v100
	v_exp_f32_e32 v101, v101
	v_exp_f32_e32 v102, v102
	v_exp_f32_e32 v103, v103
	v_add_f32_e32 v96, 1.0, v96
	v_add_f32_e32 v97, 1.0, v97
	v_add_f32_e32 v98, 1.0, v98
	v_add_f32_e32 v99, 1.0, v99
	v_add_f32_e32 v100, 1.0, v100
	v_add_f32_e32 v101, 1.0, v101
	v_add_f32_e32 v102, 1.0, v102
	v_add_f32_e32 v103, 1.0, v103
	v_rcp_f32_e32 v96, v96
	v_rcp_f32_e32 v97, v97
	v_rcp_f32_e32 v98, v98
	v_rcp_f32_e32 v99, v99
	v_rcp_f32_e32 v100, v100
	v_rcp_f32_e32 v101, v101
	v_rcp_f32_e32 v102, v102
	v_rcp_f32_e32 v103, v103
	v_lshlrev_b32_e32 v158, 16, v204
	v_and_b32_e32 v159, 0xffff0000, v204
	v_lshlrev_b32_e32 v166, 16, v212
	v_and_b32_e32 v167, 0xffff0000, v212
	v_lshlrev_b32_e32 v160, 16, v205
	v_and_b32_e32 v161, 0xffff0000, v205
	v_lshlrev_b32_e32 v168, 16, v213
	v_and_b32_e32 v169, 0xffff0000, v213
	v_lshlrev_b32_e32 v162, 16, v206
	v_and_b32_e32 v163, 0xffff0000, v206
	v_lshlrev_b32_e32 v170, 16, v214
	v_and_b32_e32 v171, 0xffff0000, v214
	v_lshlrev_b32_e32 v164, 16, v207
	v_and_b32_e32 v165, 0xffff0000, v207
	v_lshlrev_b32_e32 v172, 16, v215
	v_and_b32_e32 v173, 0xffff0000, v215
	v_pk_fma_f32 v[100:101], v[100:101], v[166:167], v[158:159]
	v_pk_fma_f32 v[102:103], v[102:103], v[168:169], v[160:161]
	v_pk_fma_f32 v[96:97], v[96:97], v[170:171], v[162:163]
	v_pk_fma_f32 v[98:99], v[98:99], v[172:173], v[164:165]
	global_store_dwordx4 v155, v[100:103], s[76:77] offset:512
	global_store_dwordx4 v155, v[96:99], s[76:77] offset:528
	s_add_u32 s72, s46, 0x48000
	s_addc_u32 s73, s47, 0
	s_add_u32 s74, s6, 0x48000
	s_addc_u32 s75, s7, 0
	global_load_dword v216, v156, s[70:71] offset:576 sc1
	global_load_dwordx4 v[200:203], v147, s[72:73]
	global_load_dwordx4 v[208:211], v147, s[74:75]
	global_load_dwordx4 v[204:207], v147, s[72:73] offset:256
	global_load_dwordx4 v[212:215], v147, s[74:75] offset:256
	s_waitcnt vmcnt(23)
	v_fmamk_f32 v157, v234, 0x3a800000, v154
	v_rsq_f32_e32 v157, v157
	s_add_u32 s76, s80, 0x20000
	s_addc_u32 s77, s81, 0
	v_mul_f32_e32 v157, 0xbfb8aa3b, v157
	v_mul_f32_e32 v88, v88, v157
	v_mul_f32_e32 v89, v89, v157
	v_mul_f32_e32 v90, v90, v157
	v_mul_f32_e32 v91, v91, v157
	v_mul_f32_e32 v92, v92, v157
	v_mul_f32_e32 v93, v93, v157
	v_mul_f32_e32 v94, v94, v157
	v_mul_f32_e32 v95, v95, v157
	v_exp_f32_e32 v88, v88
	v_exp_f32_e32 v89, v89
	v_exp_f32_e32 v90, v90
	v_exp_f32_e32 v91, v91
	v_exp_f32_e32 v92, v92
	v_exp_f32_e32 v93, v93
	v_exp_f32_e32 v94, v94
	v_exp_f32_e32 v95, v95
	v_add_f32_e32 v88, 1.0, v88
	v_add_f32_e32 v89, 1.0, v89
	v_add_f32_e32 v90, 1.0, v90
	v_add_f32_e32 v91, 1.0, v91
	v_add_f32_e32 v92, 1.0, v92
	v_add_f32_e32 v93, 1.0, v93
	v_add_f32_e32 v94, 1.0, v94
	v_add_f32_e32 v95, 1.0, v95
	v_rcp_f32_e32 v88, v88
	v_rcp_f32_e32 v89, v89
	v_rcp_f32_e32 v90, v90
	v_rcp_f32_e32 v91, v91
	v_rcp_f32_e32 v92, v92
	v_rcp_f32_e32 v93, v93
	v_rcp_f32_e32 v94, v94
	v_rcp_f32_e32 v95, v95
	v_lshlrev_b32_e32 v158, 16, v218
	v_and_b32_e32 v159, 0xffff0000, v218
	v_lshlrev_b32_e32 v166, 16, v226
	v_and_b32_e32 v167, 0xffff0000, v226
	v_lshlrev_b32_e32 v160, 16, v219
	v_and_b32_e32 v161, 0xffff0000, v219
	v_lshlrev_b32_e32 v168, 16, v227
	v_and_b32_e32 v169, 0xffff0000, v227
	v_lshlrev_b32_e32 v162, 16, v220
	v_and_b32_e32 v163, 0xffff0000, v220
	v_lshlrev_b32_e32 v170, 16, v228
;     __device__ __forceinline__ void operator()(const f32x4 (&acc)[2][2][4][2], const Unit& u, int wr, int wc, int fr, int fq) const {
;     ...
;             for (int m = 0; m < 4; ++m) { const int row = row0 + ai * HALF + m * 16; const size_t off = (size_t)row * ldc + col0;
;                 const float nrl = -1.4426950408889634f * __builtin_amdgcn_rsqf(__hip_atomic_load(rowsq + row, __ATOMIC_RELAXED, __HIP_MEMORY_SCOPE_AGENT) * (1.f / (float)ldc) + eps);
; #pragma unroll
;                 for (int bj = 0; bj < 2; ++bj) { const size_t o2 = off + bj * HALF; const u32x4 xw = *(const u32x4*)(xb + o2), g = *(const u32x4*)(pl + o2);
;                     f32x4 b0, b1, p0, p1;
;                     b0[0] = __uint_as_float(xw.x << 16); b0[1] = __uint_as_float(xw.x & 0xffff0000u); b0[2] = __uint_as_float(xw.y << 16); b0[3] = __uint_as_float(xw.y & 0xffff0000u);
;                     b1[0] = __uint_as_float(xw.z << 16); b1[1] = __uint_as_float(xw.z & 0xffff0000u); b1[2] = __uint_as_float(xw.w << 16); b1[3] = __uint_as_float(xw.w & 0xffff0000u);
;                     p0[0] = __uint_as_float(g.x << 16); p0[1] = __uint_as_float(g.x & 0xffff0000u); p0[2] = __uint_as_float(g.y << 16); p0[3] = __uint_as_float(g.y & 0xffff0000u);
;                     p1[0] = __uint_as_float(g.z << 16); p1[1] = __uint_as_float(g.z & 0xffff0000u); p1[2] = __uint_as_float(g.w << 16); p1[3] = __uint_as_float(g.w & 0xffff0000u);
;                     f32x4 s0, s1;
; #pragma unroll
;                     for (int e = 0; e < 4; ++e) { s0[e] = __builtin_amdgcn_rcpf(1.f + __builtin_amdgcn_exp2f(nrl * acc[ai][bj][m][0][e])); s1[e] = __builtin_amdgcn_rcpf(1.f + __builtin_amdgcn_exp2f(nrl * acc[ai][bj][m][1][e])); }
;                     *(f32x4*)(out + o2) = b0 + s0 * p0; *(f32x4*)(out + o2 + 4) = b1 + s1 * p1; }
	v_and_b32_e32 v171, 0xffff0000, v228
	v_lshlrev_b32_e32 v164, 16, v221
	v_and_b32_e32 v165, 0xffff0000, v221
	v_lshlrev_b32_e32 v172, 16, v229
	v_and_b32_e32 v173, 0xffff0000, v229
	v_pk_fma_f32 v[92:93], v[92:93], v[166:167], v[158:159]
	v_pk_fma_f32 v[94:95], v[94:95], v[168:169], v[160:161]
	v_pk_fma_f32 v[88:89], v[88:89], v[170:171], v[162:163]
	v_pk_fma_f32 v[90:91], v[90:91], v[172:173], v[164:165]
	global_store_dwordx4 v155, v[92:95], s[76:77]
	global_store_dwordx4 v155, v[88:91], s[76:77] offset:16
	v_mul_f32_e32 v80, v80, v157
	v_mul_f32_e32 v81, v81, v157
	v_mul_f32_e32 v82, v82, v157
	v_mul_f32_e32 v83, v83, v157
	v_mul_f32_e32 v84, v84, v157
	v_mul_f32_e32 v85, v85, v157
	v_mul_f32_e32 v86, v86, v157
	v_mul_f32_e32 v87, v87, v157
	v_exp_f32_e32 v80, v80
	v_exp_f32_e32 v81, v81
	v_exp_f32_e32 v82, v82
	v_exp_f32_e32 v83, v83
	v_exp_f32_e32 v84, v84
	v_exp_f32_e32 v85, v85
	v_exp_f32_e32 v86, v86
	v_exp_f32_e32 v87, v87
	v_add_f32_e32 v80, 1.0, v80
	v_add_f32_e32 v81, 1.0, v81
	v_add_f32_e32 v82, 1.0, v82
	v_add_f32_e32 v83, 1.0, v83
	v_add_f32_e32 v84, 1.0, v84
	v_add_f32_e32 v85, 1.0, v85
	v_add_f32_e32 v86, 1.0, v86
	v_add_f32_e32 v87, 1.0, v87
	v_rcp_f32_e32 v80, v80
	v_rcp_f32_e32 v81, v81
	v_rcp_f32_e32 v82, v82
	v_rcp_f32_e32 v83, v83
	v_rcp_f32_e32 v84, v84
	v_rcp_f32_e32 v85, v85
	v_rcp_f32_e32 v86, v86
	v_rcp_f32_e32 v87, v87
	v_lshlrev_b32_e32 v158, 16, v222
	v_and_b32_e32 v159, 0xffff0000, v222
	v_lshlrev_b32_e32 v166, 16, v230
	v_and_b32_e32 v167, 0xffff0000, v230
	v_lshlrev_b32_e32 v160, 16, v223
	v_and_b32_e32 v161, 0xffff0000, v223
	v_lshlrev_b32_e32 v168, 16, v231
	v_and_b32_e32 v169, 0xffff0000, v231
	v_lshlrev_b32_e32 v162, 16, v224
	v_and_b32_e32 v163, 0xffff0000, v224
	v_lshlrev_b32_e32 v170, 16, v232
	v_and_b32_e32 v171, 0xffff0000, v232
	v_lshlrev_b32_e32 v164, 16, v225
	v_and_b32_e32 v165, 0xffff0000, v225
	v_lshlrev_b32_e32 v172, 16, v233
	v_and_b32_e32 v173, 0xffff0000, v233
	v_pk_fma_f32 v[84:85], v[84:85], v[166:167], v[158:159]
	v_pk_fma_f32 v[86:87], v[86:87], v[168:169], v[160:161]
	v_pk_fma_f32 v[80:81], v[80:81], v[170:171], v[162:163]
	v_pk_fma_f32 v[82:83], v[82:83], v[172:173], v[164:165]
	global_store_dwordx4 v155, v[84:87], s[76:77] offset:512
	global_store_dwordx4 v155, v[80:83], s[76:77] offset:528
	s_add_u32 s72, s46, 0x50000
	s_addc_u32 s73, s47, 0
	s_add_u32 s74, s6, 0x50000
	s_addc_u32 s75, s7, 0
	global_load_dword v234, v156, s[70:71] offset:640 sc1
	global_load_dwordx4 v[218:221], v147, s[72:73]
	global_load_dwordx4 v[226:229], v147, s[74:75]
	global_load_dwordx4 v[222:225], v147, s[72:73] offset:256
	global_load_dwordx4 v[230:233], v147, s[74:75] offset:256
	s_waitcnt vmcnt(27)
	v_fmamk_f32 v157, v252, 0x3a800000, v154
	v_rsq_f32_e32 v157, v157
	s_add_u32 s76, s80, 0x30000
	s_addc_u32 s77, s81, 0
	v_mul_f32_e32 v157, 0xbfb8aa3b, v157
	v_mul_f32_e32 v72, v72, v157
	v_mul_f32_e32 v73, v73, v157
	v_mul_f32_e32 v74, v74, v157
	v_mul_f32_e32 v75, v75, v157
	v_mul_f32_e32 v76, v76, v157
	v_mul_f32_e32 v77, v77, v157
	v_mul_f32_e32 v78, v78, v157
	v_mul_f32_e32 v79, v79, v157
	v_exp_f32_e32 v72, v72
	v_exp_f32_e32 v73, v73
	v_exp_f32_e32 v74, v74
	v_exp_f32_e32 v75, v75
	v_exp_f32_e32 v76, v76
	v_exp_f32_e32 v77, v77
	v_exp_f32_e32 v78, v78
	v_exp_f32_e32 v79, v79
	v_add_f32_e32 v72, 1.0, v72
	v_add_f32_e32 v73, 1.0, v73
	v_add_f32_e32 v74, 1.0, v74
	v_add_f32_e32 v75, 1.0, v75
	v_add_f32_e32 v76, 1.0, v76
	v_add_f32_e32 v77, 1.0, v77
	v_add_f32_e32 v78, 1.0, v78
	v_add_f32_e32 v79, 1.0, v79
	v_rcp_f32_e32 v72, v72
	v_rcp_f32_e32 v73, v73
	v_rcp_f32_e32 v74, v74
	v_rcp_f32_e32 v75, v75
	v_rcp_f32_e32 v76, v76
	v_rcp_f32_e32 v77, v77
	v_rcp_f32_e32 v78, v78
	v_rcp_f32_e32 v79, v79
	v_lshlrev_b32_e32 v158, 16, v236
	v_and_b32_e32 v159, 0xffff0000, v236
	v_lshlrev_b32_e32 v166, 16, v244
	v_and_b32_e32 v167, 0xffff0000, v244
	v_lshlrev_b32_e32 v160, 16, v237
	v_and_b32_e32 v161, 0xffff0000, v237
	v_lshlrev_b32_e32 v168, 16, v245
	v_and_b32_e32 v169, 0xffff0000, v245
	v_lshlrev_b32_e32 v162, 16, v238
	v_and_b32_e32 v163, 0xffff0000, v238
	v_lshlrev_b32_e32 v170, 16, v246
	v_and_b32_e32 v171, 0xffff0000, v246
	v_lshlrev_b32_e32 v164, 16, v239
	v_and_b32_e32 v165, 0xffff0000, v239
	v_lshlrev_b32_e32 v172, 16, v247
	v_and_b32_e32 v173, 0xffff0000, v247
	v_pk_fma_f32 v[76:77], v[76:77], v[166:167], v[158:159]
	v_pk_fma_f32 v[78:79], v[78:79], v[168:169], v[160:161]
	v_pk_fma_f32 v[72:73], v[72:73], v[170:171], v[162:163]
	v_pk_fma_f32 v[74:75], v[74:75], v[172:173], v[164:165]
	global_store_dwordx4 v155, v[76:79], s[76:77]
	global_store_dwordx4 v155, v[72:75], s[76:77] offset:16
	v_mul_f32_e32 v64, v64, v157
	v_mul_f32_e32 v65, v65, v157
	v_mul_f32_e32 v66, v66, v157
	v_mul_f32_e32 v67, v67, v157
	v_mul_f32_e32 v68, v68, v157
	v_mul_f32_e32 v69, v69, v157
	v_mul_f32_e32 v70, v70, v157
	v_mul_f32_e32 v71, v71, v157
	v_exp_f32_e32 v64, v64
	v_exp_f32_e32 v65, v65
	v_exp_f32_e32 v66, v66
	v_exp_f32_e32 v67, v67
	v_exp_f32_e32 v68, v68
	v_exp_f32_e32 v69, v69
	v_exp_f32_e32 v70, v70
	v_exp_f32_e32 v71, v71
	v_add_f32_e32 v64, 1.0, v64
	v_add_f32_e32 v65, 1.0, v65
	v_add_f32_e32 v66, 1.0, v66
	v_add_f32_e32 v67, 1.0, v67
	v_add_f32_e32 v68, 1.0, v68
	v_add_f32_e32 v69, 1.0, v69
	v_add_f32_e32 v70, 1.0, v70
	v_add_f32_e32 v71, 1.0, v71
	v_rcp_f32_e32 v64, v64
	v_rcp_f32_e32 v65, v65
	v_rcp_f32_e32 v66, v66
	v_rcp_f32_e32 v67, v67
	v_rcp_f32_e32 v68, v68
	v_rcp_f32_e32 v69, v69
	v_rcp_f32_e32 v70, v70
	v_rcp_f32_e32 v71, v71
	v_lshlrev_b32_e32 v158, 16, v240
	v_and_b32_e32 v159, 0xffff0000, v240
	v_lshlrev_b32_e32 v166, 16, v248
	v_and_b32_e32 v167, 0xffff0000, v248
	v_lshlrev_b32_e32 v160, 16, v241
	v_and_b32_e32 v161, 0xffff0000, v241
	v_lshlrev_b32_e32 v168, 16, v249
	v_and_b32_e32 v169, 0xffff0000, v249
	v_lshlrev_b32_e32 v162, 16, v242
	v_and_b32_e32 v163, 0xffff0000, v242
	v_lshlrev_b32_e32 v170, 16, v250
	v_and_b32_e32 v171, 0xffff0000, v250
	v_lshlrev_b32_e32 v164, 16, v243
	v_and_b32_e32 v165, 0xffff0000, v243
	v_lshlrev_b32_e32 v172, 16, v251
	v_and_b32_e32 v173, 0xffff0000, v251
	v_pk_fma_f32 v[68:69], v[68:69], v[166:167], v[158:159]
	v_pk_fma_f32 v[70:71], v[70:71], v[168:169], v[160:161]
	v_pk_fma_f32 v[64:65], v[64:65], v[170:171], v[162:163]
	v_pk_fma_f32 v[66:67], v[66:67], v[172:173], v[164:165]
	global_store_dwordx4 v155, v[68:71], s[76:77] offset:512
	global_store_dwordx4 v155, v[64:67], s[76:77] offset:528
	s_add_u32 s72, s46, 0x58000
	s_addc_u32 s73, s47, 0
	s_add_u32 s74, s6, 0x58000
	s_addc_u32 s75, s7, 0
	global_load_dword v252, v156, s[70:71] offset:704 sc1
	global_load_dwordx4 v[236:239], v147, s[72:73]
	global_load_dwordx4 v[244:247], v147, s[74:75]
	global_load_dwordx4 v[240:243], v147, s[72:73] offset:256
	global_load_dwordx4 v[248:251], v147, s[74:75] offset:256
	s_waitcnt vmcnt(27)
;     __device__ __forceinline__ void operator()(const f32x4 (&acc)[2][2][4][2], const Unit& u, int wr, int wc, int fr, int fq) const {
;     ...
;             for (int m = 0; m < 4; ++m) { const int row = row0 + ai * HALF + m * 16; const size_t off = (size_t)row * ldc + col0;
;                 const float nrl = -1.4426950408889634f * __builtin_amdgcn_rsqf(__hip_atomic_load(rowsq + row, __ATOMIC_RELAXED, __HIP_MEMORY_SCOPE_AGENT) * (1.f / (float)ldc) + eps);
; #pragma unroll
;                 for (int bj = 0; bj < 2; ++bj) { const size_t o2 = off + bj * HALF; const u32x4 xw = *(const u32x4*)(xb + o2), g = *(const u32x4*)(pl + o2);
;                     f32x4 b0, b1, p0, p1;
;                     b0[0] = __uint_as_float(xw.x << 16); b0[1] = __uint_as_float(xw.x & 0xffff0000u); b0[2] = __uint_as_float(xw.y << 16); b0[3] = __uint_as_float(xw.y & 0xffff0000u);
;                     b1[0] = __uint_as_float(xw.z << 16); b1[1] = __uint_as_float(xw.z & 0xffff0000u); b1[2] = __uint_as_float(xw.w << 16); b1[3] = __uint_as_float(xw.w & 0xffff0000u);
;                     p0[0] = __uint_as_float(g.x << 16); p0[1] = __uint_as_float(g.x & 0xffff0000u); p0[2] = __uint_as_float(g.y << 16); p0[3] = __uint_as_float(g.y & 0xffff0000u);
;                     p1[0] = __uint_as_float(g.z << 16); p1[1] = __uint_as_float(g.z & 0xffff0000u); p1[2] = __uint_as_float(g.w << 16); p1[3] = __uint_as_float(g.w & 0xffff0000u);
;                     f32x4 s0, s1;
; #pragma unroll
;                     for (int e = 0; e < 4; ++e) { s0[e] = __builtin_amdgcn_rcpf(1.f + __builtin_amdgcn_exp2f(nrl * acc[ai][bj][m][0][e])); s1[e] = __builtin_amdgcn_rcpf(1.f + __builtin_amdgcn_exp2f(nrl * acc[ai][bj][m][1][e])); }
;                     *(f32x4*)(out + o2) = b0 + s0 * p0; *(f32x4*)(out + o2 + 4) = b1 + s1 * p1; }
	v_fmamk_f32 v157, v198, 0x3a800000, v154
	v_rsq_f32_e32 v157, v157
	s_add_u32 s76, s80, 0x80000
	s_addc_u32 s77, s81, 0
	v_mul_f32_e32 v157, 0xbfb8aa3b, v157
	v_mul_f32_e32 v56, v56, v157
	v_mul_f32_e32 v57, v57, v157
	v_mul_f32_e32 v58, v58, v157
	v_mul_f32_e32 v59, v59, v157
	v_mul_f32_e32 v60, v60, v157
	v_mul_f32_e32 v61, v61, v157
	v_mul_f32_e32 v62, v62, v157
	v_mul_f32_e32 v63, v63, v157
	v_exp_f32_e32 v56, v56
	v_exp_f32_e32 v57, v57
	v_exp_f32_e32 v58, v58
	v_exp_f32_e32 v59, v59
	v_exp_f32_e32 v60, v60
	v_exp_f32_e32 v61, v61
	v_exp_f32_e32 v62, v62
	v_exp_f32_e32 v63, v63
	v_add_f32_e32 v56, 1.0, v56
	v_add_f32_e32 v57, 1.0, v57
	v_add_f32_e32 v58, 1.0, v58
	v_add_f32_e32 v59, 1.0, v59
	v_add_f32_e32 v60, 1.0, v60
	v_add_f32_e32 v61, 1.0, v61
	v_add_f32_e32 v62, 1.0, v62
	v_add_f32_e32 v63, 1.0, v63
	v_rcp_f32_e32 v56, v56
	v_rcp_f32_e32 v57, v57
	v_rcp_f32_e32 v58, v58
	v_rcp_f32_e32 v59, v59
	v_rcp_f32_e32 v60, v60
	v_rcp_f32_e32 v61, v61
	v_rcp_f32_e32 v62, v62
	v_rcp_f32_e32 v63, v63
	v_lshlrev_b32_e32 v158, 16, v182
	v_and_b32_e32 v159, 0xffff0000, v182
	v_lshlrev_b32_e32 v166, 16, v190
	v_and_b32_e32 v167, 0xffff0000, v190
	v_lshlrev_b32_e32 v160, 16, v183
	v_and_b32_e32 v161, 0xffff0000, v183
	v_lshlrev_b32_e32 v168, 16, v191
	v_and_b32_e32 v169, 0xffff0000, v191
	v_lshlrev_b32_e32 v162, 16, v184
	v_and_b32_e32 v163, 0xffff0000, v184
	v_lshlrev_b32_e32 v170, 16, v192
	v_and_b32_e32 v171, 0xffff0000, v192
	v_lshlrev_b32_e32 v164, 16, v185
	v_and_b32_e32 v165, 0xffff0000, v185
	v_lshlrev_b32_e32 v172, 16, v193
	v_and_b32_e32 v173, 0xffff0000, v193
	v_pk_fma_f32 v[60:61], v[60:61], v[166:167], v[158:159]
	v_pk_fma_f32 v[62:63], v[62:63], v[168:169], v[160:161]
	v_pk_fma_f32 v[56:57], v[56:57], v[170:171], v[162:163]
	v_pk_fma_f32 v[58:59], v[58:59], v[172:173], v[164:165]
	global_store_dwordx4 v155, v[60:63], s[76:77]
	global_store_dwordx4 v155, v[56:59], s[76:77] offset:16
	v_mul_f32_e32 v48, v48, v157
	v_mul_f32_e32 v49, v49, v157
	v_mul_f32_e32 v50, v50, v157
	v_mul_f32_e32 v51, v51, v157
	v_mul_f32_e32 v52, v52, v157
	v_mul_f32_e32 v53, v53, v157
	v_mul_f32_e32 v54, v54, v157
	v_mul_f32_e32 v55, v55, v157
	v_exp_f32_e32 v48, v48
	v_exp_f32_e32 v49, v49
	v_exp_f32_e32 v50, v50
	v_exp_f32_e32 v51, v51
	v_exp_f32_e32 v52, v52
	v_exp_f32_e32 v53, v53
	v_exp_f32_e32 v54, v54
	v_exp_f32_e32 v55, v55
	v_add_f32_e32 v48, 1.0, v48
	v_add_f32_e32 v49, 1.0, v49
	v_add_f32_e32 v50, 1.0, v50
	v_add_f32_e32 v51, 1.0, v51
	v_add_f32_e32 v52, 1.0, v52
	v_add_f32_e32 v53, 1.0, v53
	v_add_f32_e32 v54, 1.0, v54
	v_add_f32_e32 v55, 1.0, v55
	v_rcp_f32_e32 v48, v48
	v_rcp_f32_e32 v49, v49
	v_rcp_f32_e32 v50, v50
	v_rcp_f32_e32 v51, v51
	v_rcp_f32_e32 v52, v52
	v_rcp_f32_e32 v53, v53
	v_rcp_f32_e32 v54, v54
	v_rcp_f32_e32 v55, v55
	v_lshlrev_b32_e32 v158, 16, v186
	v_and_b32_e32 v159, 0xffff0000, v186
	v_lshlrev_b32_e32 v166, 16, v194
	v_and_b32_e32 v167, 0xffff0000, v194
	v_lshlrev_b32_e32 v160, 16, v187
	v_and_b32_e32 v161, 0xffff0000, v187
	v_lshlrev_b32_e32 v168, 16, v195
	v_and_b32_e32 v169, 0xffff0000, v195
	v_lshlrev_b32_e32 v162, 16, v188
	v_and_b32_e32 v163, 0xffff0000, v188
	v_lshlrev_b32_e32 v170, 16, v196
	v_and_b32_e32 v171, 0xffff0000, v196
	v_lshlrev_b32_e32 v164, 16, v189
	v_and_b32_e32 v165, 0xffff0000, v189
	v_lshlrev_b32_e32 v172, 16, v197
	v_and_b32_e32 v173, 0xffff0000, v197
	v_pk_fma_f32 v[52:53], v[52:53], v[166:167], v[158:159]
	v_pk_fma_f32 v[54:55], v[54:55], v[168:169], v[160:161]
	v_pk_fma_f32 v[48:49], v[48:49], v[170:171], v[162:163]
	v_pk_fma_f32 v[50:51], v[50:51], v[172:173], v[164:165]
	global_store_dwordx4 v155, v[52:55], s[76:77] offset:512
	global_store_dwordx4 v155, v[48:51], s[76:77] offset:528
	s_waitcnt vmcnt(22)
	v_fmamk_f32 v157, v216, 0x3a800000, v154
	v_rsq_f32_e32 v157, v157
	s_add_u32 s76, s80, 0x90000
	s_addc_u32 s77, s81, 0
	v_mul_f32_e32 v157, 0xbfb8aa3b, v157
	v_mul_f32_e32 v40, v40, v157
	v_mul_f32_e32 v41, v41, v157
	v_mul_f32_e32 v42, v42, v157
	v_mul_f32_e32 v43, v43, v157
	v_mul_f32_e32 v44, v44, v157
	v_mul_f32_e32 v45, v45, v157
	v_mul_f32_e32 v46, v46, v157
	v_mul_f32_e32 v47, v47, v157
	v_exp_f32_e32 v40, v40
	v_exp_f32_e32 v41, v41
	v_exp_f32_e32 v42, v42
	v_exp_f32_e32 v43, v43
	v_exp_f32_e32 v44, v44
	v_exp_f32_e32 v45, v45
	v_exp_f32_e32 v46, v46
	v_exp_f32_e32 v47, v47
	v_add_f32_e32 v40, 1.0, v40
	v_add_f32_e32 v41, 1.0, v41
	v_add_f32_e32 v42, 1.0, v42
	v_add_f32_e32 v43, 1.0, v43
	v_add_f32_e32 v44, 1.0, v44
	v_add_f32_e32 v45, 1.0, v45
	v_add_f32_e32 v46, 1.0, v46
	v_add_f32_e32 v47, 1.0, v47
	v_rcp_f32_e32 v40, v40
	v_rcp_f32_e32 v41, v41
	v_rcp_f32_e32 v42, v42
	v_rcp_f32_e32 v43, v43
	v_rcp_f32_e32 v44, v44
	v_rcp_f32_e32 v45, v45
	v_rcp_f32_e32 v46, v46
	v_rcp_f32_e32 v47, v47
	v_lshlrev_b32_e32 v158, 16, v200
	v_and_b32_e32 v159, 0xffff0000, v200
	v_lshlrev_b32_e32 v166, 16, v208
	v_and_b32_e32 v167, 0xffff0000, v208
	v_lshlrev_b32_e32 v160, 16, v201
	v_and_b32_e32 v161, 0xffff0000, v201
	v_lshlrev_b32_e32 v168, 16, v209
	v_and_b32_e32 v169, 0xffff0000, v209
	v_lshlrev_b32_e32 v162, 16, v202
	v_and_b32_e32 v163, 0xffff0000, v202
	v_lshlrev_b32_e32 v170, 16, v210
	v_and_b32_e32 v171, 0xffff0000, v210
	v_lshlrev_b32_e32 v164, 16, v203
	v_and_b32_e32 v165, 0xffff0000, v203
	v_lshlrev_b32_e32 v172, 16, v211
	v_and_b32_e32 v173, 0xffff0000, v211
	v_pk_fma_f32 v[44:45], v[44:45], v[166:167], v[158:159]
	v_pk_fma_f32 v[46:47], v[46:47], v[168:169], v[160:161]
	v_pk_fma_f32 v[40:41], v[40:41], v[170:171], v[162:163]
	v_pk_fma_f32 v[42:43], v[42:43], v[172:173], v[164:165]
	global_store_dwordx4 v155, v[44:47], s[76:77]
	global_store_dwordx4 v155, v[40:43], s[76:77] offset:16
;     __device__ __forceinline__ void operator()(const f32x4 (&acc)[2][2][4][2], const Unit& u, int wr, int wc, int fr, int fq) const {
;     ...
;             for (int m = 0; m < 4; ++m) { const int row = row0 + ai * HALF + m * 16; const size_t off = (size_t)row * ldc + col0;
;                 const float nrl = -1.4426950408889634f * __builtin_amdgcn_rsqf(__hip_atomic_load(rowsq + row, __ATOMIC_RELAXED, __HIP_MEMORY_SCOPE_AGENT) * (1.f / (float)ldc) + eps);
; #pragma unroll
;                 for (int bj = 0; bj < 2; ++bj) { const size_t o2 = off + bj * HALF; const u32x4 xw = *(const u32x4*)(xb + o2), g = *(const u32x4*)(pl + o2);
;                     f32x4 b0, b1, p0, p1;
;                     b0[0] = __uint_as_float(xw.x << 16); b0[1] = __uint_as_float(xw.x & 0xffff0000u); b0[2] = __uint_as_float(xw.y << 16); b0[3] = __uint_as_float(xw.y & 0xffff0000u);
;                     b1[0] = __uint_as_float(xw.z << 16); b1[1] = __uint_as_float(xw.z & 0xffff0000u); b1[2] = __uint_as_float(xw.w << 16); b1[3] = __uint_as_float(xw.w & 0xffff0000u);
;                     p0[0] = __uint_as_float(g.x << 16); p0[1] = __uint_as_float(g.x & 0xffff0000u); p0[2] = __uint_as_float(g.y << 16); p0[3] = __uint_as_float(g.y & 0xffff0000u);
;                     p1[0] = __uint_as_float(g.z << 16); p1[1] = __uint_as_float(g.z & 0xffff0000u); p1[2] = __uint_as_float(g.w << 16); p1[3] = __uint_as_float(g.w & 0xffff0000u);
;                     f32x4 s0, s1;
; #pragma unroll
;                     for (int e = 0; e < 4; ++e) { s0[e] = __builtin_amdgcn_rcpf(1.f + __builtin_amdgcn_exp2f(nrl * acc[ai][bj][m][0][e])); s1[e] = __builtin_amdgcn_rcpf(1.f + __builtin_amdgcn_exp2f(nrl * acc[ai][bj][m][1][e])); }
;                     *(f32x4*)(out + o2) = b0 + s0 * p0; *(f32x4*)(out + o2 + 4) = b1 + s1 * p1; }
	v_mul_f32_e32 v32, v32, v157
	v_mul_f32_e32 v33, v33, v157
	v_mul_f32_e32 v34, v34, v157
	v_mul_f32_e32 v35, v35, v157
	v_mul_f32_e32 v36, v36, v157
	v_mul_f32_e32 v37, v37, v157
	v_mul_f32_e32 v38, v38, v157
	v_mul_f32_e32 v39, v39, v157
	v_exp_f32_e32 v32, v32
	v_exp_f32_e32 v33, v33
	v_exp_f32_e32 v34, v34
	v_exp_f32_e32 v35, v35
	v_exp_f32_e32 v36, v36
	v_exp_f32_e32 v37, v37
	v_exp_f32_e32 v38, v38
	v_exp_f32_e32 v39, v39
	v_add_f32_e32 v32, 1.0, v32
	v_add_f32_e32 v33, 1.0, v33
	v_add_f32_e32 v34, 1.0, v34
	v_add_f32_e32 v35, 1.0, v35
	v_add_f32_e32 v36, 1.0, v36
	v_add_f32_e32 v37, 1.0, v37
	v_add_f32_e32 v38, 1.0, v38
	v_add_f32_e32 v39, 1.0, v39
	v_rcp_f32_e32 v32, v32
	v_rcp_f32_e32 v33, v33
	v_rcp_f32_e32 v34, v34
	v_rcp_f32_e32 v35, v35
	v_rcp_f32_e32 v36, v36
	v_rcp_f32_e32 v37, v37
	v_rcp_f32_e32 v38, v38
	v_rcp_f32_e32 v39, v39
	v_lshlrev_b32_e32 v158, 16, v204
	v_and_b32_e32 v159, 0xffff0000, v204
	v_lshlrev_b32_e32 v166, 16, v212
	v_and_b32_e32 v167, 0xffff0000, v212
	v_lshlrev_b32_e32 v160, 16, v205
	v_and_b32_e32 v161, 0xffff0000, v205
	v_lshlrev_b32_e32 v168, 16, v213
	v_and_b32_e32 v169, 0xffff0000, v213
	v_lshlrev_b32_e32 v162, 16, v206
	v_and_b32_e32 v163, 0xffff0000, v206
	v_lshlrev_b32_e32 v170, 16, v214
	v_and_b32_e32 v171, 0xffff0000, v214
	v_lshlrev_b32_e32 v164, 16, v207
	v_and_b32_e32 v165, 0xffff0000, v207
	v_lshlrev_b32_e32 v172, 16, v215
	v_and_b32_e32 v173, 0xffff0000, v215
	v_pk_fma_f32 v[36:37], v[36:37], v[166:167], v[158:159]
	v_pk_fma_f32 v[38:39], v[38:39], v[168:169], v[160:161]
	v_pk_fma_f32 v[32:33], v[32:33], v[170:171], v[162:163]
	v_pk_fma_f32 v[34:35], v[34:35], v[172:173], v[164:165]
	global_store_dwordx4 v155, v[36:39], s[76:77] offset:512
	global_store_dwordx4 v155, v[32:35], s[76:77] offset:528
	s_waitcnt vmcnt(17)
	v_fmamk_f32 v157, v234, 0x3a800000, v154
	v_rsq_f32_e32 v157, v157
	s_add_u32 s76, s80, 0xa0000
	s_addc_u32 s77, s81, 0
	v_mul_f32_e32 v157, 0xbfb8aa3b, v157
	v_mul_f32_e32 v24, v24, v157
	v_mul_f32_e32 v25, v25, v157
	v_mul_f32_e32 v26, v26, v157
	v_mul_f32_e32 v27, v27, v157
	v_mul_f32_e32 v28, v28, v157
	v_mul_f32_e32 v29, v29, v157
	v_mul_f32_e32 v30, v30, v157
	v_mul_f32_e32 v31, v31, v157
	v_exp_f32_e32 v24, v24
	v_exp_f32_e32 v25, v25
	v_exp_f32_e32 v26, v26
	v_exp_f32_e32 v27, v27
	v_exp_f32_e32 v28, v28
	v_exp_f32_e32 v29, v29
	v_exp_f32_e32 v30, v30
	v_exp_f32_e32 v31, v31
	v_add_f32_e32 v24, 1.0, v24
	v_add_f32_e32 v25, 1.0, v25
	v_add_f32_e32 v26, 1.0, v26
	v_add_f32_e32 v27, 1.0, v27
	v_add_f32_e32 v28, 1.0, v28
	v_add_f32_e32 v29, 1.0, v29
	v_add_f32_e32 v30, 1.0, v30
	v_add_f32_e32 v31, 1.0, v31
	v_rcp_f32_e32 v24, v24
	v_rcp_f32_e32 v25, v25
	v_rcp_f32_e32 v26, v26
	v_rcp_f32_e32 v27, v27
	v_rcp_f32_e32 v28, v28
	v_rcp_f32_e32 v29, v29
	v_rcp_f32_e32 v30, v30
	v_rcp_f32_e32 v31, v31
	v_lshlrev_b32_e32 v158, 16, v218
	v_and_b32_e32 v159, 0xffff0000, v218
	v_lshlrev_b32_e32 v166, 16, v226
	v_and_b32_e32 v167, 0xffff0000, v226
	v_lshlrev_b32_e32 v160, 16, v219
	v_and_b32_e32 v161, 0xffff0000, v219
	v_lshlrev_b32_e32 v168, 16, v227
	v_and_b32_e32 v169, 0xffff0000, v227
	v_lshlrev_b32_e32 v162, 16, v220
	v_and_b32_e32 v163, 0xffff0000, v220
	v_lshlrev_b32_e32 v170, 16, v228
	v_and_b32_e32 v171, 0xffff0000, v228
	v_lshlrev_b32_e32 v164, 16, v221
	v_and_b32_e32 v165, 0xffff0000, v221
	v_lshlrev_b32_e32 v172, 16, v229
	v_and_b32_e32 v173, 0xffff0000, v229
	v_pk_fma_f32 v[28:29], v[28:29], v[166:167], v[158:159]
	v_pk_fma_f32 v[30:31], v[30:31], v[168:169], v[160:161]
	v_pk_fma_f32 v[24:25], v[24:25], v[170:171], v[162:163]
	v_pk_fma_f32 v[26:27], v[26:27], v[172:173], v[164:165]
	global_store_dwordx4 v155, v[28:31], s[76:77]
	global_store_dwordx4 v155, v[24:27], s[76:77] offset:16
	v_mul_f32_e32 v16, v16, v157
	v_mul_f32_e32 v17, v17, v157
	v_mul_f32_e32 v18, v18, v157
	v_mul_f32_e32 v19, v19, v157
	v_mul_f32_e32 v20, v20, v157
	v_mul_f32_e32 v21, v21, v157
	v_mul_f32_e32 v22, v22, v157
	v_mul_f32_e32 v23, v23, v157
	v_exp_f32_e32 v16, v16
	v_exp_f32_e32 v17, v17
	v_exp_f32_e32 v18, v18
	v_exp_f32_e32 v19, v19
	v_exp_f32_e32 v20, v20
	v_exp_f32_e32 v21, v21
	v_exp_f32_e32 v22, v22
	v_exp_f32_e32 v23, v23
	v_add_f32_e32 v16, 1.0, v16
	v_add_f32_e32 v17, 1.0, v17
	v_add_f32_e32 v18, 1.0, v18
	v_add_f32_e32 v19, 1.0, v19
	v_add_f32_e32 v20, 1.0, v20
	v_add_f32_e32 v21, 1.0, v21
	v_add_f32_e32 v22, 1.0, v22
	v_add_f32_e32 v23, 1.0, v23
	v_rcp_f32_e32 v16, v16
	v_rcp_f32_e32 v17, v17
	v_rcp_f32_e32 v18, v18
	v_rcp_f32_e32 v19, v19
	v_rcp_f32_e32 v20, v20
	v_rcp_f32_e32 v21, v21
	v_rcp_f32_e32 v22, v22
	v_rcp_f32_e32 v23, v23
	v_lshlrev_b32_e32 v158, 16, v222
	v_and_b32_e32 v159, 0xffff0000, v222
	v_lshlrev_b32_e32 v166, 16, v230
	v_and_b32_e32 v167, 0xffff0000, v230
	v_lshlrev_b32_e32 v160, 16, v223
	v_and_b32_e32 v161, 0xffff0000, v223
	v_lshlrev_b32_e32 v168, 16, v231
	v_and_b32_e32 v169, 0xffff0000, v231
	v_lshlrev_b32_e32 v162, 16, v224
	v_and_b32_e32 v163, 0xffff0000, v224
	v_lshlrev_b32_e32 v170, 16, v232
	v_and_b32_e32 v171, 0xffff0000, v232
	v_lshlrev_b32_e32 v164, 16, v225
	v_and_b32_e32 v165, 0xffff0000, v225
	v_lshlrev_b32_e32 v172, 16, v233
	v_and_b32_e32 v173, 0xffff0000, v233
	v_pk_fma_f32 v[20:21], v[20:21], v[166:167], v[158:159]
	v_pk_fma_f32 v[22:23], v[22:23], v[168:169], v[160:161]
	v_pk_fma_f32 v[16:17], v[16:17], v[170:171], v[162:163]
	v_pk_fma_f32 v[18:19], v[18:19], v[172:173], v[164:165]
	global_store_dwordx4 v155, v[20:23], s[76:77] offset:512
	global_store_dwordx4 v155, v[16:19], s[76:77] offset:528
	s_waitcnt vmcnt(12)
;     __device__ __forceinline__ void operator()(const f32x4 (&acc)[2][2][4][2], const Unit& u, int wr, int wc, int fr, int fq) const {
;     ...
;             for (int m = 0; m < 4; ++m) { const int row = row0 + ai * HALF + m * 16; const size_t off = (size_t)row * ldc + col0;
;                 const float nrl = -1.4426950408889634f * __builtin_amdgcn_rsqf(__hip_atomic_load(rowsq + row, __ATOMIC_RELAXED, __HIP_MEMORY_SCOPE_AGENT) * (1.f / (float)ldc) + eps);
; #pragma unroll
;                 for (int bj = 0; bj < 2; ++bj) { const size_t o2 = off + bj * HALF; const u32x4 xw = *(const u32x4*)(xb + o2), g = *(const u32x4*)(pl + o2);
;                     f32x4 b0, b1, p0, p1;
;                     b0[0] = __uint_as_float(xw.x << 16); b0[1] = __uint_as_float(xw.x & 0xffff0000u); b0[2] = __uint_as_float(xw.y << 16); b0[3] = __uint_as_float(xw.y & 0xffff0000u);
;                     b1[0] = __uint_as_float(xw.z << 16); b1[1] = __uint_as_float(xw.z & 0xffff0000u); b1[2] = __uint_as_float(xw.w << 16); b1[3] = __uint_as_float(xw.w & 0xffff0000u);
;                     p0[0] = __uint_as_float(g.x << 16); p0[1] = __uint_as_float(g.x & 0xffff0000u); p0[2] = __uint_as_float(g.y << 16); p0[3] = __uint_as_float(g.y & 0xffff0000u);
;                     p1[0] = __uint_as_float(g.z << 16); p1[1] = __uint_as_float(g.z & 0xffff0000u); p1[2] = __uint_as_float(g.w << 16); p1[3] = __uint_as_float(g.w & 0xffff0000u);
;                     f32x4 s0, s1;
; #pragma unroll
;                     for (int e = 0; e < 4; ++e) { s0[e] = __builtin_amdgcn_rcpf(1.f + __builtin_amdgcn_exp2f(nrl * acc[ai][bj][m][0][e])); s1[e] = __builtin_amdgcn_rcpf(1.f + __builtin_amdgcn_exp2f(nrl * acc[ai][bj][m][1][e])); }
;                     *(f32x4*)(out + o2) = b0 + s0 * p0; *(f32x4*)(out + o2 + 4) = b1 + s1 * p1; }
; template <class Epi, class Sched, bool ALIGN_EPI = false, bool SP2 = false>
; __device__ __forceinline__ void gemm_phase(PG8_LAS unsigned char* lds, const Gemm g, const Sched& S, const Epi& E) {
;     ...
;         if (!has_next) break;
; #pragma unroll
;         for (int a = 0; a < 2; ++a)
; #pragma unroll
;             for (int b = 0; b < 2; ++b)
; #pragma unroll
;                 for (int m = 0; m < 4; ++m)
; #pragma unroll
;                     for (int n = 0; n < 2; ++n) acc[a][b][m][n] = (f32x4){0.f, 0.f, 0.f, 0.f};
;         cur = nxt; cA = nA; cB = nB; ++ui;
	v_fmamk_f32 v157, v252, 0x3a800000, v154
	v_rsq_f32_e32 v157, v157
	s_add_u32 s76, s80, 0xb0000
	s_addc_u32 s77, s81, 0
	v_mul_f32_e32 v157, 0xbfb8aa3b, v157
	v_mul_f32_e32 v8, v8, v157
	v_mul_f32_e32 v9, v9, v157
	v_mul_f32_e32 v10, v10, v157
	v_mul_f32_e32 v11, v11, v157
	v_mul_f32_e32 v12, v12, v157
	v_mul_f32_e32 v13, v13, v157
	v_mul_f32_e32 v14, v14, v157
	v_mul_f32_e32 v15, v15, v157
	v_exp_f32_e32 v8, v8
	v_exp_f32_e32 v9, v9
	v_exp_f32_e32 v10, v10
	v_exp_f32_e32 v11, v11
	v_exp_f32_e32 v12, v12
	v_exp_f32_e32 v13, v13
	v_exp_f32_e32 v14, v14
	v_exp_f32_e32 v15, v15
	v_add_f32_e32 v8, 1.0, v8
	v_add_f32_e32 v9, 1.0, v9
	v_add_f32_e32 v10, 1.0, v10
	v_add_f32_e32 v11, 1.0, v11
	v_add_f32_e32 v12, 1.0, v12
	v_add_f32_e32 v13, 1.0, v13
	v_add_f32_e32 v14, 1.0, v14
	v_add_f32_e32 v15, 1.0, v15
	v_rcp_f32_e32 v8, v8
	v_rcp_f32_e32 v9, v9
	v_rcp_f32_e32 v10, v10
	v_rcp_f32_e32 v11, v11
	v_rcp_f32_e32 v12, v12
	v_rcp_f32_e32 v13, v13
	v_rcp_f32_e32 v14, v14
	v_rcp_f32_e32 v15, v15
	v_lshlrev_b32_e32 v158, 16, v236
	v_and_b32_e32 v159, 0xffff0000, v236
	v_lshlrev_b32_e32 v166, 16, v244
	v_and_b32_e32 v167, 0xffff0000, v244
	v_lshlrev_b32_e32 v160, 16, v237
	v_and_b32_e32 v161, 0xffff0000, v237
	v_lshlrev_b32_e32 v168, 16, v245
	v_and_b32_e32 v169, 0xffff0000, v245
	v_lshlrev_b32_e32 v162, 16, v238
	v_and_b32_e32 v163, 0xffff0000, v238
	v_lshlrev_b32_e32 v170, 16, v246
	v_and_b32_e32 v171, 0xffff0000, v246
	v_lshlrev_b32_e32 v164, 16, v239
	v_and_b32_e32 v165, 0xffff0000, v239
	v_lshlrev_b32_e32 v172, 16, v247
	v_and_b32_e32 v173, 0xffff0000, v247
	v_pk_fma_f32 v[12:13], v[12:13], v[166:167], v[158:159]
	v_pk_fma_f32 v[14:15], v[14:15], v[168:169], v[160:161]
	v_pk_fma_f32 v[8:9], v[8:9], v[170:171], v[162:163]
	v_pk_fma_f32 v[10:11], v[10:11], v[172:173], v[164:165]
	global_store_dwordx4 v155, v[12:15], s[76:77]
	global_store_dwordx4 v155, v[8:11], s[76:77] offset:16
	v_mul_f32_e32 v0, v0, v157
	v_mul_f32_e32 v1, v1, v157
	v_mul_f32_e32 v2, v2, v157
	v_mul_f32_e32 v3, v3, v157
	v_mul_f32_e32 v4, v4, v157
	v_mul_f32_e32 v5, v5, v157
	v_mul_f32_e32 v6, v6, v157
	v_mul_f32_e32 v7, v7, v157
	v_exp_f32_e32 v0, v0
	v_exp_f32_e32 v1, v1
	v_exp_f32_e32 v2, v2
	v_exp_f32_e32 v3, v3
	v_exp_f32_e32 v4, v4
	v_exp_f32_e32 v5, v5
	v_exp_f32_e32 v6, v6
	v_exp_f32_e32 v7, v7
	v_add_f32_e32 v0, 1.0, v0
	v_add_f32_e32 v1, 1.0, v1
	v_add_f32_e32 v2, 1.0, v2
	v_add_f32_e32 v3, 1.0, v3
	v_add_f32_e32 v4, 1.0, v4
	v_add_f32_e32 v5, 1.0, v5
	v_add_f32_e32 v6, 1.0, v6
	v_add_f32_e32 v7, 1.0, v7
	v_rcp_f32_e32 v0, v0
	v_rcp_f32_e32 v1, v1
	v_rcp_f32_e32 v2, v2
	v_rcp_f32_e32 v3, v3
	v_rcp_f32_e32 v4, v4
	v_rcp_f32_e32 v5, v5
	v_rcp_f32_e32 v6, v6
	v_rcp_f32_e32 v7, v7
	v_lshlrev_b32_e32 v158, 16, v240
	v_and_b32_e32 v159, 0xffff0000, v240
	v_lshlrev_b32_e32 v166, 16, v248
	v_and_b32_e32 v167, 0xffff0000, v248
	v_lshlrev_b32_e32 v160, 16, v241
	v_and_b32_e32 v161, 0xffff0000, v241
	v_lshlrev_b32_e32 v168, 16, v249
	v_and_b32_e32 v169, 0xffff0000, v249
	v_lshlrev_b32_e32 v162, 16, v242
	v_and_b32_e32 v163, 0xffff0000, v242
	v_lshlrev_b32_e32 v170, 16, v250
	v_and_b32_e32 v171, 0xffff0000, v250
	v_lshlrev_b32_e32 v164, 16, v243
	v_and_b32_e32 v165, 0xffff0000, v243
	v_lshlrev_b32_e32 v172, 16, v251
	v_and_b32_e32 v173, 0xffff0000, v251
	v_pk_fma_f32 v[4:5], v[4:5], v[166:167], v[158:159]
	v_pk_fma_f32 v[6:7], v[6:7], v[168:169], v[160:161]
	v_pk_fma_f32 v[0:1], v[0:1], v[170:171], v[162:163]
	v_pk_fma_f32 v[2:3], v[2:3], v[172:173], v[164:165]
	global_store_dwordx4 v155, v[4:7], s[76:77] offset:512
	global_store_dwordx4 v155, v[0:3], s[76:77] offset:528
	s_cbranch_vccnz .LBB0_716
	s_andn2_b64 vcc, exec, s[4:5]
	s_cbranch_vccnz .LBB0_715
	s_barrier
	s_branch .LBB0_715
